# P9 residual epilogue: x loads pipelined four row groups deep with counted waits
# speedup vs baseline: 1.0106x; 1.0071x over previous
; #define PG8_STAGE(bufoff, gbase) PG8_STAGE_(bufoff, gbase, voffA)
; #define PG8_STAGEB(bufoff, gbase) PG8_STAGE_(bufoff, gbase, voffB)
; #define PG8_LDA(dst, b, h) do { _Pragma("unroll") for (int m = 0; m < 4; ++m) _Pragma("unroll") for (int k = 0; k < 2; ++k) dst[m][k] = *(const LAS bf16x8*)(lds + PG8_SA(b, h) + aoff + m * 2048 + k * 1024); } while (0)
; #define PG8_LDB(dst, b, h) do { _Pragma("unroll") for (int n = 0; n < 2; ++n) _Pragma("unroll") for (int k = 0; k < 2; ++k) dst[n][k] = *(const LAS bf16x8*)(lds + PG8_SB(b, h) + boff + n * 2048 + k * 1024); } while (0)
; #define PG8_MMA(ai, bj, At, Bt) do { __builtin_amdgcn_s_setprio(1); _Pragma("unroll") for (int m = 0; m < 4; ++m) _Pragma("unroll") for (int n = 0; n < 2; ++n) _Pragma("unroll") for (int k = 0; k < 2; ++k) \
;         acc[ai][bj][m][n] = __builtin_amdgcn_mfma_f32_16x16x32_bf16(Bt[n][k], At[m][k], acc[ai][bj][m][n], 0, 0, 0); __builtin_amdgcn_s_setprio(0); } while (0)
; #define PG8_WAIT_V(n) asm volatile("s_waitcnt vmcnt(" #n ")" ::: "memory")
; #define PG8_WAIT_L(n) asm volatile("s_waitcnt lgkmcnt(" #n ")" ::: "memory")
; #define PG8_BAR __builtin_amdgcn_s_barrier()
; #define PG8_SCHED __builtin_amdgcn_sched_barrier(0)
; template <class Epi>
; __device__ __forceinline__ void gemm_phase(LAS unsigned char* lds, const Gemm g, const StaticOrder& S, const Epi& E) {
;     ...
;             PG8_LDB(B0, 0, 0); PG8_SCHED; PG8_LDA(At, 0, 0); PG8_STAGE(PG8_SA(1, 1), a1 + hstep);
;             PG8_WAIT_L(8); PG8_BAR; PG8_WAIT_L(0); PG8_MMA(0, 0, At, B0); PG8_BAR; PG8_SCHED;
;             PG8_LDB(B1, 0, 1); PG8_STAGEB(PG8_SB(0, 0), b2);
;             PG8_BAR; PG8_WAIT_L(0); PG8_MMA(0, 1, At, B1); PG8_BAR;
;             PG8_LDA(At, 0, 1); PG8_STAGE(PG8_SA(0, 0), a2);
;             PG8_BAR; PG8_WAIT_L(0); PG8_MMA(1, 0, At, B0); PG8_BAR; PG8_SCHED;
;             PG8_STAGEB(PG8_SB(0, 1), b2 + hstep);
;             PG8_WAIT_V(6); PG8_BAR; PG8_MMA(1, 1, At, B1); PG8_BAR;
.LBB0_1447:
	ds_read_b128 v[144:147], v140
	ds_read_b128 v[148:151], v140 offset:1024
	ds_read_b128 v[152:155], v140 offset:2048
	ds_read_b128 v[156:159], v140 offset:3072
	ds_read_b128 v[160:163], v143
	ds_read_b128 v[164:167], v143 offset:1024
	ds_read_b128 v[168:171], v143 offset:2048
	ds_read_b128 v[172:175], v143 offset:3072
	ds_read_b128 v[176:179], v143 offset:4096
	ds_read_b128 v[188:191], v143 offset:5120
	ds_read_b128 v[192:195], v143 offset:6144
	global_load_lds_dwordx4 v136, s[30:31]
	s_add_i32 m0, s55, 0xe000
	ds_read_b128 v[196:199], v143 offset:7168
	global_load_lds_dwordx4 v138, s[30:31]
	s_waitcnt lgkmcnt(8)
	s_barrier
	s_waitcnt lgkmcnt(0)
	s_setprio 1
	v_mfma_f32_16x16x32_bf16 v[126:129], v[144:147], v[160:163], v[126:129]
	v_mfma_f32_16x16x32_bf16 v[122:125], v[152:155], v[160:163], v[122:125]
	s_add_i32 s89, 0, 0x14000
	v_mfma_f32_16x16x32_bf16 v[110:113], v[144:147], v[168:171], v[110:113]
	s_add_i32 s58, s58, s54
	v_mfma_f32_16x16x32_bf16 v[106:109], v[152:155], v[168:171], v[106:109]
	s_mov_b32 m0, s58
	v_mfma_f32_16x16x32_bf16 v[94:97], v[144:147], v[176:179], v[94:97]
	v_mfma_f32_16x16x32_bf16 v[90:93], v[152:155], v[176:179], v[90:93]
	v_mfma_f32_16x16x32_bf16 v[78:81], v[144:147], v[192:195], v[78:81]
	v_mfma_f32_16x16x32_bf16 v[74:77], v[152:155], v[192:195], v[74:77]
	v_mfma_f32_16x16x32_bf16 v[126:129], v[148:151], v[164:167], v[126:129]
	v_mfma_f32_16x16x32_bf16 v[122:125], v[156:159], v[164:167], v[122:125]
	v_mfma_f32_16x16x32_bf16 v[110:113], v[148:151], v[172:175], v[110:113]
	v_mfma_f32_16x16x32_bf16 v[106:109], v[156:159], v[172:175], v[106:109]
	v_mfma_f32_16x16x32_bf16 v[94:97], v[148:151], v[188:191], v[94:97]
	v_mfma_f32_16x16x32_bf16 v[90:93], v[156:159], v[188:191], v[90:93]
	v_mfma_f32_16x16x32_bf16 v[78:81], v[148:151], v[196:199], v[78:81]
	v_mfma_f32_16x16x32_bf16 v[74:77], v[156:159], v[196:199], v[74:77]
	s_setprio 0
	s_barrier
	ds_read_b128 v[200:203], v141
	ds_read_b128 v[206:209], v141 offset:1024
	ds_read_b128 v[210:213], v141 offset:2048
	global_load_lds_dwordx4 v0, s[20:21]
	s_add_i32 m0, s58, 0x2000
	ds_read_b128 v[214:217], v141 offset:3072
	global_load_lds_dwordx4 v130, s[20:21]
	s_barrier
	s_waitcnt lgkmcnt(0)
	s_setprio 1
	v_mfma_f32_16x16x32_bf16 v[118:121], v[200:203], v[160:163], v[118:121]
	v_mfma_f32_16x16x32_bf16 v[114:117], v[210:213], v[160:163], v[114:117]
	v_mfma_f32_16x16x32_bf16 v[102:105], v[200:203], v[168:171], v[102:105]
	v_mfma_f32_16x16x32_bf16 v[98:101], v[210:213], v[168:171], v[98:101]
	v_mfma_f32_16x16x32_bf16 v[86:89], v[200:203], v[176:179], v[86:89]
	v_mfma_f32_16x16x32_bf16 v[82:85], v[210:213], v[176:179], v[82:85]
	v_mfma_f32_16x16x32_bf16 v[70:73], v[200:203], v[192:195], v[70:73]
	v_mfma_f32_16x16x32_bf16 v[66:69], v[210:213], v[192:195], v[66:69]
	v_mfma_f32_16x16x32_bf16 v[118:121], v[206:209], v[164:167], v[118:121]
	v_mfma_f32_16x16x32_bf16 v[114:117], v[214:217], v[164:167], v[114:117]
	v_mfma_f32_16x16x32_bf16 v[102:105], v[206:209], v[172:175], v[102:105]
	v_mfma_f32_16x16x32_bf16 v[98:101], v[214:217], v[172:175], v[98:101]
	v_mfma_f32_16x16x32_bf16 v[86:89], v[206:209], v[188:191], v[86:89]
	v_mfma_f32_16x16x32_bf16 v[82:85], v[214:217], v[188:191], v[82:85]
	v_mfma_f32_16x16x32_bf16 v[70:73], v[206:209], v[196:199], v[70:73]
	v_mfma_f32_16x16x32_bf16 v[66:69], v[214:217], v[196:199], v[66:69]
	s_setprio 0
	s_mov_b32 m0, s55
	s_barrier
	ds_read_b128 v[160:163], v143 offset:16384
	ds_read_b128 v[164:167], v143 offset:17408
	ds_read_b128 v[168:171], v143 offset:18432
	ds_read_b128 v[172:175], v143 offset:19456
	ds_read_b128 v[176:179], v143 offset:20480
	ds_read_b128 v[188:191], v143 offset:21504
	ds_read_b128 v[192:195], v143 offset:22528
	global_load_lds_dwordx4 v134, s[48:49]
	s_mov_b32 m0, s62
	ds_read_b128 v[196:199], v143 offset:23552
	global_load_lds_dwordx4 v132, s[48:49]
	s_barrier
	s_waitcnt lgkmcnt(0)
	s_setprio 1
	v_mfma_f32_16x16x32_bf16 v[62:65], v[144:147], v[160:163], v[62:65]
	v_mfma_f32_16x16x32_bf16 v[58:61], v[152:155], v[160:163], v[58:61]
	s_add_u32 s58, s20, 0x80000
	v_mfma_f32_16x16x32_bf16 v[46:49], v[144:147], v[168:171], v[46:49]
	s_addc_u32 s59, s21, 0
	v_mfma_f32_16x16x32_bf16 v[42:45], v[152:155], v[168:171], v[42:45]
	s_add_i32 s89, s89, s54
	v_mfma_f32_16x16x32_bf16 v[30:33], v[144:147], v[176:179], v[30:33]
	s_mov_b32 m0, s89
	v_mfma_f32_16x16x32_bf16 v[26:29], v[152:155], v[176:179], v[26:29]
	v_mfma_f32_16x16x32_bf16 v[14:17], v[144:147], v[192:195], v[14:17]
	v_mfma_f32_16x16x32_bf16 v[10:13], v[152:155], v[192:195], v[10:13]
	v_mfma_f32_16x16x32_bf16 v[62:65], v[148:151], v[164:167], v[62:65]
	v_mfma_f32_16x16x32_bf16 v[58:61], v[156:159], v[164:167], v[58:61]
	v_mfma_f32_16x16x32_bf16 v[46:49], v[148:151], v[172:175], v[46:49]
	v_mfma_f32_16x16x32_bf16 v[42:45], v[156:159], v[172:175], v[42:45]
	v_mfma_f32_16x16x32_bf16 v[30:33], v[148:151], v[188:191], v[30:33]
	v_mfma_f32_16x16x32_bf16 v[26:29], v[156:159], v[188:191], v[26:29]
	v_mfma_f32_16x16x32_bf16 v[14:17], v[148:151], v[196:199], v[14:17]
	v_mfma_f32_16x16x32_bf16 v[10:13], v[156:159], v[196:199], v[10:13]
	s_setprio 0
	s_barrier
	global_load_lds_dwordx4 v0, s[58:59]
	s_add_i32 m0, s89, 0x2000
	s_nop 0
	global_load_lds_dwordx4 v130, s[58:59]
	s_waitcnt vmcnt(6)
	s_barrier
; #define PG8_STAGE(bufoff, gbase) PG8_STAGE_(bufoff, gbase, voffA)
; #define PG8_STAGEB(bufoff, gbase) PG8_STAGE_(bufoff, gbase, voffB)
; #define PG8_LDA(dst, b, h) do { _Pragma("unroll") for (int m = 0; m < 4; ++m) _Pragma("unroll") for (int k = 0; k < 2; ++k) dst[m][k] = *(const LAS bf16x8*)(lds + PG8_SA(b, h) + aoff + m * 2048 + k * 1024); } while (0)
; #define PG8_LDB(dst, b, h) do { _Pragma("unroll") for (int n = 0; n < 2; ++n) _Pragma("unroll") for (int k = 0; k < 2; ++k) dst[n][k] = *(const LAS bf16x8*)(lds + PG8_SB(b, h) + boff + n * 2048 + k * 1024); } while (0)
; #define PG8_MMA(ai, bj, At, Bt) do { __builtin_amdgcn_s_setprio(1); _Pragma("unroll") for (int m = 0; m < 4; ++m) _Pragma("unroll") for (int n = 0; n < 2; ++n) _Pragma("unroll") for (int k = 0; k < 2; ++k) \
;         acc[ai][bj][m][n] = __builtin_amdgcn_mfma_f32_16x16x32_bf16(Bt[n][k], At[m][k], acc[ai][bj][m][n], 0, 0, 0); __builtin_amdgcn_s_setprio(0); } while (0)
; #define PG8_WAIT_V(n) asm volatile("s_waitcnt vmcnt(" #n ")" ::: "memory")
; #define PG8_WAIT_L(n) asm volatile("s_waitcnt lgkmcnt(" #n ")" ::: "memory")
; #define PG8_BAR __builtin_amdgcn_s_barrier()
; #define PG8_SCHED __builtin_amdgcn_sched_barrier(0)
; template <class Epi>
; __device__ __forceinline__ void gemm_phase(LAS unsigned char* lds, const Gemm g, const StaticOrder& S, const Epi& E) {
;     ...
;             PG8_WAIT_V(6); PG8_BAR; PG8_MMA(1, 1, At, B1); PG8_BAR;
;             PG8_LDB(B0, 1, 0); PG8_SCHED; PG8_LDA(At, 1, 0); PG8_STAGE(PG8_SA(0, 1), a2 + hstep);
;             PG8_WAIT_L(8); PG8_BAR; PG8_WAIT_L(0); PG8_MMA(0, 0, At, B0); PG8_BAR; PG8_SCHED;
;             PG8_LDB(B1, 1, 1); PG8_STAGEB(PG8_SB(1, 0), b3);
;             PG8_BAR; PG8_WAIT_L(0); PG8_MMA(0, 1, At, B1); PG8_BAR;
;             PG8_LDA(At, 1, 1); PG8_STAGE(PG8_SA(1, 0), a3);
;             PG8_BAR; PG8_WAIT_L(0); PG8_MMA(1, 0, At, B0); PG8_BAR; PG8_SCHED;
	s_setprio 1
	v_mfma_f32_16x16x32_bf16 v[54:57], v[200:203], v[160:163], v[54:57]
	v_mfma_f32_16x16x32_bf16 v[50:53], v[210:213], v[160:163], v[50:53]
	s_add_i32 s58, 0, 0x18000
	v_mfma_f32_16x16x32_bf16 v[38:41], v[200:203], v[168:171], v[38:41]
	s_add_u32 s48, s48, 0x80000
	v_mfma_f32_16x16x32_bf16 v[34:37], v[210:213], v[168:171], v[34:37]
	s_addc_u32 s49, s49, 0
	v_mfma_f32_16x16x32_bf16 v[22:25], v[200:203], v[176:179], v[22:25]
	s_mov_b32 m0, s63
	v_mfma_f32_16x16x32_bf16 v[18:21], v[210:213], v[176:179], v[18:21]
	v_mfma_f32_16x16x32_bf16 v[6:9], v[200:203], v[192:195], v[6:9]
	v_mfma_f32_16x16x32_bf16 v[2:5], v[210:213], v[192:195], v[2:5]
	v_mfma_f32_16x16x32_bf16 v[54:57], v[206:209], v[164:167], v[54:57]
	v_mfma_f32_16x16x32_bf16 v[50:53], v[214:217], v[164:167], v[50:53]
	v_mfma_f32_16x16x32_bf16 v[38:41], v[206:209], v[172:175], v[38:41]
	v_mfma_f32_16x16x32_bf16 v[34:37], v[214:217], v[172:175], v[34:37]
	v_mfma_f32_16x16x32_bf16 v[22:25], v[206:209], v[188:191], v[22:25]
	v_mfma_f32_16x16x32_bf16 v[18:21], v[214:217], v[188:191], v[18:21]
	v_mfma_f32_16x16x32_bf16 v[6:9], v[206:209], v[196:199], v[6:9]
	v_mfma_f32_16x16x32_bf16 v[2:5], v[214:217], v[196:199], v[2:5]
	s_setprio 0
	s_barrier
	ds_read_b128 v[144:147], v182
	ds_read_b128 v[148:151], v182 offset:1024
	ds_read_b128 v[152:155], v182 offset:2048
	ds_read_b128 v[156:159], v182 offset:3072
	ds_read_b128 v[160:163], v143 offset:32768
	ds_read_b128 v[164:167], v143 offset:33792
	ds_read_b128 v[168:171], v143 offset:34816
	ds_read_b128 v[172:175], v143 offset:35840
	ds_read_b128 v[176:179], v143 offset:36864
	ds_read_b128 v[188:191], v143 offset:37888
	ds_read_b128 v[192:195], v143 offset:38912
	global_load_lds_dwordx4 v134, s[48:49]
	s_mov_b32 m0, s66
	ds_read_b128 v[196:199], v143 offset:39936
	global_load_lds_dwordx4 v132, s[48:49]
	s_waitcnt lgkmcnt(8)
	s_barrier
	s_waitcnt lgkmcnt(0)
	s_setprio 1
	v_mfma_f32_16x16x32_bf16 v[126:129], v[144:147], v[160:163], v[126:129]
	v_mfma_f32_16x16x32_bf16 v[122:125], v[152:155], v[160:163], v[122:125]
	s_add_i32 s48, 0, 0x1c000
	v_mfma_f32_16x16x32_bf16 v[110:113], v[144:147], v[168:171], v[110:113]
	s_add_i32 s49, s58, s54
	v_mfma_f32_16x16x32_bf16 v[106:109], v[152:155], v[168:171], v[106:109]
	s_add_i32 m0, s49, 0xffffff80
	v_mfma_f32_16x16x32_bf16 v[94:97], v[144:147], v[176:179], v[94:97]
	v_mfma_f32_16x16x32_bf16 v[90:93], v[152:155], v[176:179], v[90:93]
	v_mfma_f32_16x16x32_bf16 v[78:81], v[144:147], v[192:195], v[78:81]
	v_mfma_f32_16x16x32_bf16 v[74:77], v[152:155], v[192:195], v[74:77]
	v_mfma_f32_16x16x32_bf16 v[126:129], v[148:151], v[164:167], v[126:129]
	v_mfma_f32_16x16x32_bf16 v[122:125], v[156:159], v[164:167], v[122:125]
	v_mfma_f32_16x16x32_bf16 v[110:113], v[148:151], v[172:175], v[110:113]
	v_mfma_f32_16x16x32_bf16 v[106:109], v[156:159], v[172:175], v[106:109]
	v_mfma_f32_16x16x32_bf16 v[94:97], v[148:151], v[188:191], v[94:97]
	v_mfma_f32_16x16x32_bf16 v[90:93], v[156:159], v[188:191], v[90:93]
	v_mfma_f32_16x16x32_bf16 v[78:81], v[148:151], v[196:199], v[78:81]
	v_mfma_f32_16x16x32_bf16 v[74:77], v[156:159], v[196:199], v[74:77]
	s_setprio 0
	s_barrier
	ds_read_b128 v[200:203], v183
	ds_read_b128 v[206:209], v183 offset:1024
	ds_read_b128 v[210:213], v183 offset:2048
	global_load_lds_dwordx4 v0, s[20:21] offset:128
	s_add_i32 m0, s49, 0x1f80
	ds_read_b128 v[214:217], v183 offset:3072
	global_load_lds_dwordx4 v130, s[20:21] offset:128
	s_barrier
	s_waitcnt lgkmcnt(0)
	s_setprio 1
	v_mfma_f32_16x16x32_bf16 v[118:121], v[200:203], v[160:163], v[118:121]
	v_mfma_f32_16x16x32_bf16 v[114:117], v[210:213], v[160:163], v[114:117]
	v_mfma_f32_16x16x32_bf16 v[102:105], v[200:203], v[168:171], v[102:105]
	v_mfma_f32_16x16x32_bf16 v[98:101], v[210:213], v[168:171], v[98:101]
	v_mfma_f32_16x16x32_bf16 v[86:89], v[200:203], v[176:179], v[86:89]
	v_mfma_f32_16x16x32_bf16 v[82:85], v[210:213], v[176:179], v[82:85]
	v_mfma_f32_16x16x32_bf16 v[70:73], v[200:203], v[192:195], v[70:73]
	v_mfma_f32_16x16x32_bf16 v[66:69], v[210:213], v[192:195], v[66:69]
	v_mfma_f32_16x16x32_bf16 v[118:121], v[206:209], v[164:167], v[118:121]
	v_mfma_f32_16x16x32_bf16 v[114:117], v[214:217], v[164:167], v[114:117]
	v_mfma_f32_16x16x32_bf16 v[102:105], v[206:209], v[172:175], v[102:105]
	v_mfma_f32_16x16x32_bf16 v[98:101], v[214:217], v[172:175], v[98:101]
	v_mfma_f32_16x16x32_bf16 v[86:89], v[206:209], v[188:191], v[86:89]
	v_mfma_f32_16x16x32_bf16 v[82:85], v[214:217], v[188:191], v[82:85]
	v_mfma_f32_16x16x32_bf16 v[70:73], v[206:209], v[196:199], v[70:73]
	v_mfma_f32_16x16x32_bf16 v[66:69], v[214:217], v[196:199], v[66:69]
	s_setprio 0
	s_mov_b32 m0, s67
	s_barrier
	ds_read_b128 v[160:163], v143 offset:49152
	ds_read_b128 v[164:167], v143 offset:50176
	ds_read_b128 v[168:171], v143 offset:51200
	ds_read_b128 v[172:175], v143 offset:52224
	ds_read_b128 v[176:179], v143 offset:53248
	ds_read_b128 v[188:191], v143 offset:54272
	ds_read_b128 v[192:195], v143 offset:55296
	global_load_lds_dwordx4 v134, s[100:101]
	s_mov_b32 m0, s80
	ds_read_b128 v[196:199], v143 offset:56320
	global_load_lds_dwordx4 v132, s[100:101]
	s_barrier
; __device__ __forceinline__ int fresh_tid() { int t = threadIdx.x; asm volatile("" : "+v"(t)); return t; }
; #define PG8_STAGEB(bufoff, gbase) PG8_STAGE_(bufoff, gbase, voffB)
; #define PG8_MMA(ai, bj, At, Bt) do { __builtin_amdgcn_s_setprio(1); _Pragma("unroll") for (int m = 0; m < 4; ++m) _Pragma("unroll") for (int n = 0; n < 2; ++n) _Pragma("unroll") for (int k = 0; k < 2; ++k) \
;         acc[ai][bj][m][n] = __builtin_amdgcn_mfma_f32_16x16x32_bf16(Bt[n][k], At[m][k], acc[ai][bj][m][n], 0, 0, 0); __builtin_amdgcn_s_setprio(0); } while (0)
; #define PG8_WAIT_V(n) asm volatile("s_waitcnt vmcnt(" #n ")" ::: "memory")
; #define PG8_WAIT_L(n) asm volatile("s_waitcnt lgkmcnt(" #n ")" ::: "memory")
; #define PG8_BAR __builtin_amdgcn_s_barrier()
; #define PG8_SCHED __builtin_amdgcn_sched_barrier(0)
; template <class Epi>
; __device__ __forceinline__ void gemm_phase(LAS unsigned char* lds, const Gemm g, const StaticOrder& S, const Epi& E) {
;     ...
;             PG8_BAR; PG8_WAIT_L(0); PG8_MMA(1, 0, At, B0); PG8_BAR; PG8_SCHED;
;             PG8_STAGEB(PG8_SB(1, 1), b3 + hstep);
;             PG8_WAIT_V(6); PG8_BAR; PG8_MMA(1, 1, At, B1); PG8_BAR;
;         }
;         { const int t2 = fresh_tid(); const int w2 = __builtin_amdgcn_readfirstlane(t2 >> 6); E(acc, cur, w2 >> 2, w2 & 3, t2 & 15, (t2 >> 4) & 3); }
;     __device__ __forceinline__ void operator()(AccT& acc, const Unit& u, int wr, int wc, int fr, int fq) const {
;         int row0 = u.pm * 256 + wr * 64 + fr, col0 = u.pn * 256 + wc * 32 + 8 * fq;
;         asm volatile("" : "+v"(row0), "+v"(col0));
; #pragma unroll
;         for (int ai = 0; ai < 2; ++ai)
; #pragma unroll
;             for (int m = 0; m < 4; ++m) { const size_t off = (size_t)(row0 + ai * 128 + m * 16) * DM + col0;
; #pragma unroll
;                 for (int bj = 0; bj < 2; ++bj) { const f32x4 x0 = *(const f32x4*)(xin + off + bj * 128), x1 = *(const f32x4*)(xin + off + bj * 128 + 4);
;                     __builtin_nontemporal_store(x0 + acc[ai][bj][m][0], (f32x4*)(out + off + bj * 128)); __builtin_nontemporal_store(x1 + acc[ai][bj][m][1], (f32x4*)(out + off + bj * 128 + 4)); } }
	s_waitcnt lgkmcnt(0)
	s_setprio 1
	v_mfma_f32_16x16x32_bf16 v[62:65], v[144:147], v[160:163], v[62:65]
	v_mfma_f32_16x16x32_bf16 v[58:61], v[152:155], v[160:163], v[58:61]
	s_add_u32 s20, s20, 0x80080
	v_mfma_f32_16x16x32_bf16 v[46:49], v[144:147], v[168:171], v[46:49]
	s_addc_u32 s21, s21, 0
	v_mfma_f32_16x16x32_bf16 v[42:45], v[152:155], v[168:171], v[42:45]
	s_add_i32 s48, s48, s54
	v_mfma_f32_16x16x32_bf16 v[30:33], v[144:147], v[176:179], v[30:33]
	s_mov_b32 m0, s48
	v_mfma_f32_16x16x32_bf16 v[26:29], v[152:155], v[176:179], v[26:29]
	v_mfma_f32_16x16x32_bf16 v[14:17], v[144:147], v[192:195], v[14:17]
	v_mfma_f32_16x16x32_bf16 v[10:13], v[152:155], v[192:195], v[10:13]
	v_mfma_f32_16x16x32_bf16 v[62:65], v[148:151], v[164:167], v[62:65]
	v_mfma_f32_16x16x32_bf16 v[58:61], v[156:159], v[164:167], v[58:61]
	v_mfma_f32_16x16x32_bf16 v[46:49], v[148:151], v[172:175], v[46:49]
	v_mfma_f32_16x16x32_bf16 v[42:45], v[156:159], v[172:175], v[42:45]
	v_mfma_f32_16x16x32_bf16 v[30:33], v[148:151], v[188:191], v[30:33]
	v_mfma_f32_16x16x32_bf16 v[26:29], v[156:159], v[188:191], v[26:29]
	v_mfma_f32_16x16x32_bf16 v[14:17], v[148:151], v[196:199], v[14:17]
	v_mfma_f32_16x16x32_bf16 v[10:13], v[156:159], v[196:199], v[10:13]
	s_setprio 0
	s_barrier
	global_load_lds_dwordx4 v0, s[20:21]
	s_add_i32 m0, s48, 0x2000
	s_nop 0
	global_load_lds_dwordx4 v130, s[20:21]
	s_waitcnt vmcnt(6)
	s_barrier
	s_setprio 1
	v_mfma_f32_16x16x32_bf16 v[54:57], v[200:203], v[160:163], v[54:57]
	v_mfma_f32_16x16x32_bf16 v[50:53], v[210:213], v[160:163], v[50:53]
	s_add_i32 s88, s88, 2
	v_mfma_f32_16x16x32_bf16 v[38:41], v[200:203], v[168:171], v[38:41]
	s_add_u32 s30, s30, 0x100
	v_mfma_f32_16x16x32_bf16 v[34:37], v[210:213], v[168:171], v[34:37]
	s_addc_u32 s31, s31, 0
	v_mfma_f32_16x16x32_bf16 v[22:25], v[200:203], v[176:179], v[22:25]
	s_add_u32 s86, s86, 0x100
	v_mfma_f32_16x16x32_bf16 v[18:21], v[210:213], v[176:179], v[18:21]
	s_addc_u32 s87, s87, 0
	v_mfma_f32_16x16x32_bf16 v[6:9], v[200:203], v[192:195], v[6:9]
	s_add_u32 s20, s30, 0xfff80080
	v_mfma_f32_16x16x32_bf16 v[2:5], v[210:213], v[192:195], v[2:5]
	s_addc_u32 s21, s31, -1
	v_mfma_f32_16x16x32_bf16 v[54:57], v[206:209], v[164:167], v[54:57]
	s_add_i32 s58, 0, 0x10000
	v_mfma_f32_16x16x32_bf16 v[50:53], v[214:217], v[164:167], v[50:53]
	s_cmp_eq_u32 s88, 28
	v_mfma_f32_16x16x32_bf16 v[38:41], v[206:209], v[172:175], v[38:41]
	s_cselect_b32 s49, s25, s21
	v_mfma_f32_16x16x32_bf16 v[34:37], v[214:217], v[172:175], v[34:37]
	s_cselect_b32 s48, s84, s20
	v_mfma_f32_16x16x32_bf16 v[22:25], v[206:209], v[188:191], v[22:25]
	s_cselect_b32 s21, s7, s87
	v_mfma_f32_16x16x32_bf16 v[18:21], v[214:217], v[188:191], v[18:21]
	s_cselect_b32 s20, s85, s86
	v_mfma_f32_16x16x32_bf16 v[6:9], v[206:209], v[196:199], v[6:9]
	s_add_u32 s100, s48, s16
	v_mfma_f32_16x16x32_bf16 v[2:5], v[214:217], v[196:199], v[2:5]
	s_addc_u32 s101, s49, s17
	s_add_i32 m0, s55, 0xc000
	s_setprio 0
	s_cmp_gt_u32 s88, 29
	s_barrier
	s_cbranch_scc0 .LBB0_1447
	v_mov_b32_e32 v141, v250
	s_lshl_b32 s20, s83, 8
	v_readfirstlane_b32 s7, v141
	s_ashr_i32 s21, s7, 2
	s_andn2_b32 s21, s21, 63
	s_lshr_b32 s7, s7, 1
	s_add_i32 s21, s21, s20
	s_lshl_b32 s20, s82, 8
	s_and_b32 s7, s7, 0x60
	v_and_or_b32 v140, v141, 15, s21
	s_or_b32 s7, s7, s20
	v_lshrrev_b32_e32 v141, 1, v141
	v_and_or_b32 v144, v141, 24, s7
	s_mov_b64 s[20:21], 0x20000
	v_ashrrev_i32_e32 v141, 31, v140
	v_ashrrev_i32_e32 v145, 31, v144
	v_lshlrev_b64 v[140:141], 11, v[140:141]
	v_lshl_add_u64 v[140:141], v[140:141], 0, v[144:145]
	v_lshlrev_b64 v[140:141], 2, v[140:141]
	v_lshl_add_u64 v[152:153], s[0:1], 0, v[140:141]
	v_mov_b32_e32 v218, v152
	v_mov_b32_e32 v219, v153
	v_lshl_add_u64 v[220:221], s[44:45], 0, v[140:141]
	s_and_b64 vcc, exec, s[42:43]
	s_mov_b32 s82, s6
	s_mov_b32 s83, s24
	s_mov_b64 s[30:31], s[34:35]
	s_mov_b32 s86, 0x3fb8aa3b
	s_mov_b32 s89, 0x42b17218
	global_load_dwordx4 v[144:147], v[218:219], off offset:0
	global_load_dwordx4 v[148:151], v[218:219], off offset:16
	global_load_dwordx4 v[152:155], v[218:219], off offset:512
	global_load_dwordx4 v[156:159], v[218:219], off offset:528
	s_mov_b64 s[20:21], 0x20000
	v_lshl_add_u64 v[218:219], v[218:219], 0, s[20:21]
	global_load_dwordx4 v[160:163], v[218:219], off offset:0
	global_load_dwordx4 v[164:167], v[218:219], off offset:16
	global_load_dwordx4 v[168:171], v[218:219], off offset:512
	global_load_dwordx4 v[172:175], v[218:219], off offset:528
	s_mov_b64 s[20:21], 0x20000
	v_lshl_add_u64 v[218:219], v[218:219], 0, s[20:21]
	global_load_dwordx4 v[176:179], v[218:219], off offset:0
	global_load_dwordx4 v[188:191], v[218:219], off offset:16
	global_load_dwordx4 v[192:195], v[218:219], off offset:512
	global_load_dwordx4 v[196:199], v[218:219], off offset:528
	s_mov_b64 s[20:21], 0x20000
	v_lshl_add_u64 v[218:219], v[218:219], 0, s[20:21]
	global_load_dwordx4 v[200:203], v[218:219], off offset:0
	global_load_dwordx4 v[206:209], v[218:219], off offset:16
	global_load_dwordx4 v[210:213], v[218:219], off offset:512
	global_load_dwordx4 v[214:217], v[218:219], off offset:528
	s_mov_b64 s[20:21], 0xa0000
	v_lshl_add_u64 v[218:219], v[218:219], 0, s[20:21]
	s_waitcnt vmcnt(12)
;     __device__ __forceinline__ void operator()(AccT& acc, const Unit& u, int wr, int wc, int fr, int fq) const {
;     ...
; #pragma unroll
;         for (int ai = 0; ai < 2; ++ai)
; #pragma unroll
;             for (int m = 0; m < 4; ++m) { const size_t off = (size_t)(row0 + ai * 128 + m * 16) * DM + col0;
; #pragma unroll
;                 for (int bj = 0; bj < 2; ++bj) { const f32x4 x0 = *(const f32x4*)(xin + off + bj * 128), x1 = *(const f32x4*)(xin + off + bj * 128 + 4);
;                     __builtin_nontemporal_store(x0 + acc[ai][bj][m][0], (f32x4*)(out + off + bj * 128)); __builtin_nontemporal_store(x1 + acc[ai][bj][m][1], (f32x4*)(out + off + bj * 128 + 4)); } }
	v_pk_add_f32 v[126:127], v[126:127], v[144:145]
	v_pk_add_f32 v[128:129], v[128:129], v[146:147]
	v_pk_add_f32 v[122:123], v[122:123], v[148:149]
	v_pk_add_f32 v[124:125], v[124:125], v[150:151]
	global_store_dwordx4 v[220:221], v[126:129], off nt
	global_store_dwordx4 v[220:221], v[122:125], off offset:16 nt
	v_pk_add_f32 v[118:119], v[118:119], v[152:153]
	v_pk_add_f32 v[120:121], v[120:121], v[154:155]
	v_pk_add_f32 v[114:115], v[114:115], v[156:157]
	v_pk_add_f32 v[116:117], v[116:117], v[158:159]
	global_store_dwordx4 v[220:221], v[118:121], off offset:512 nt
	global_store_dwordx4 v[220:221], v[114:117], off offset:528 nt
	s_mov_b64 s[20:21], 0x20000
	v_lshl_add_u64 v[220:221], v[220:221], 0, s[20:21]
	global_load_dwordx4 v[144:147], v[218:219], off offset:0
	global_load_dwordx4 v[148:151], v[218:219], off offset:16
	global_load_dwordx4 v[152:155], v[218:219], off offset:512
	global_load_dwordx4 v[156:159], v[218:219], off offset:528
	s_mov_b64 s[20:21], 0x20000
	v_lshl_add_u64 v[218:219], v[218:219], 0, s[20:21]
	s_waitcnt vmcnt(16)
	v_pk_add_f32 v[110:111], v[110:111], v[160:161]
	v_pk_add_f32 v[112:113], v[112:113], v[162:163]
	v_pk_add_f32 v[106:107], v[106:107], v[164:165]
	v_pk_add_f32 v[108:109], v[108:109], v[166:167]
	global_store_dwordx4 v[220:221], v[110:113], off nt
	global_store_dwordx4 v[220:221], v[106:109], off offset:16 nt
	v_pk_add_f32 v[102:103], v[102:103], v[168:169]
	v_pk_add_f32 v[104:105], v[104:105], v[170:171]
	v_pk_add_f32 v[98:99], v[98:99], v[172:173]
	v_pk_add_f32 v[100:101], v[100:101], v[174:175]
	global_store_dwordx4 v[220:221], v[102:105], off offset:512 nt
	global_store_dwordx4 v[220:221], v[98:101], off offset:528 nt
	s_mov_b64 s[20:21], 0x20000
	v_lshl_add_u64 v[220:221], v[220:221], 0, s[20:21]
	global_load_dwordx4 v[160:163], v[218:219], off offset:0
	global_load_dwordx4 v[164:167], v[218:219], off offset:16
	global_load_dwordx4 v[168:171], v[218:219], off offset:512
	global_load_dwordx4 v[172:175], v[218:219], off offset:528
	s_mov_b64 s[20:21], 0x20000
	v_lshl_add_u64 v[218:219], v[218:219], 0, s[20:21]
	s_waitcnt vmcnt(20)
	v_pk_add_f32 v[94:95], v[94:95], v[176:177]
	v_pk_add_f32 v[96:97], v[96:97], v[178:179]
	v_pk_add_f32 v[90:91], v[90:91], v[188:189]
	v_pk_add_f32 v[92:93], v[92:93], v[190:191]
	global_store_dwordx4 v[220:221], v[94:97], off nt
	global_store_dwordx4 v[220:221], v[90:93], off offset:16 nt
	v_pk_add_f32 v[86:87], v[86:87], v[192:193]
	v_pk_add_f32 v[88:89], v[88:89], v[194:195]
	v_pk_add_f32 v[82:83], v[82:83], v[196:197]
	v_pk_add_f32 v[84:85], v[84:85], v[198:199]
	global_store_dwordx4 v[220:221], v[86:89], off offset:512 nt
	global_store_dwordx4 v[220:221], v[82:85], off offset:528 nt
	s_mov_b64 s[20:21], 0x20000
	v_lshl_add_u64 v[220:221], v[220:221], 0, s[20:21]
	global_load_dwordx4 v[176:179], v[218:219], off offset:0
	global_load_dwordx4 v[188:191], v[218:219], off offset:16
	global_load_dwordx4 v[192:195], v[218:219], off offset:512
	global_load_dwordx4 v[196:199], v[218:219], off offset:528
	s_mov_b64 s[20:21], 0x20000
	v_lshl_add_u64 v[218:219], v[218:219], 0, s[20:21]
	s_waitcnt vmcnt(24)
	v_pk_add_f32 v[78:79], v[78:79], v[200:201]
	v_pk_add_f32 v[80:81], v[80:81], v[202:203]
	v_pk_add_f32 v[74:75], v[74:75], v[206:207]
	v_pk_add_f32 v[76:77], v[76:77], v[208:209]
	global_store_dwordx4 v[220:221], v[78:81], off nt
	global_store_dwordx4 v[220:221], v[74:77], off offset:16 nt
	v_pk_add_f32 v[70:71], v[70:71], v[210:211]
	v_pk_add_f32 v[72:73], v[72:73], v[212:213]
	v_pk_add_f32 v[66:67], v[66:67], v[214:215]
	v_pk_add_f32 v[68:69], v[68:69], v[216:217]
	global_store_dwordx4 v[220:221], v[70:73], off offset:512 nt
	global_store_dwordx4 v[220:221], v[66:69], off offset:528 nt
	s_mov_b64 s[20:21], 0xa0000
	v_lshl_add_u64 v[220:221], v[220:221], 0, s[20:21]
	global_load_dwordx4 v[200:203], v[218:219], off offset:0
	global_load_dwordx4 v[206:209], v[218:219], off offset:16
	global_load_dwordx4 v[210:213], v[218:219], off offset:512
	global_load_dwordx4 v[214:217], v[218:219], off offset:528
	s_waitcnt vmcnt(24)
	v_pk_add_f32 v[62:63], v[62:63], v[144:145]
	v_pk_add_f32 v[64:65], v[64:65], v[146:147]
	v_pk_add_f32 v[58:59], v[58:59], v[148:149]
	v_pk_add_f32 v[60:61], v[60:61], v[150:151]
	global_store_dwordx4 v[220:221], v[62:65], off nt
	global_store_dwordx4 v[220:221], v[58:61], off offset:16 nt
	v_pk_add_f32 v[54:55], v[54:55], v[152:153]
	v_pk_add_f32 v[56:57], v[56:57], v[154:155]
	v_pk_add_f32 v[50:51], v[50:51], v[156:157]
	v_pk_add_f32 v[52:53], v[52:53], v[158:159]
	global_store_dwordx4 v[220:221], v[54:57], off offset:512 nt
	global_store_dwordx4 v[220:221], v[50:53], off offset:528 nt
	s_mov_b64 s[20:21], 0x20000
	v_lshl_add_u64 v[220:221], v[220:221], 0, s[20:21]
	s_waitcnt vmcnt(20)
	v_pk_add_f32 v[46:47], v[46:47], v[160:161]
	v_pk_add_f32 v[48:49], v[48:49], v[162:163]
	v_pk_add_f32 v[42:43], v[42:43], v[164:165]
	v_pk_add_f32 v[44:45], v[44:45], v[166:167]
	global_store_dwordx4 v[220:221], v[46:49], off nt
	global_store_dwordx4 v[220:221], v[42:45], off offset:16 nt
	v_pk_add_f32 v[38:39], v[38:39], v[168:169]
	v_pk_add_f32 v[40:41], v[40:41], v[170:171]
	v_pk_add_f32 v[34:35], v[34:35], v[172:173]
	v_pk_add_f32 v[36:37], v[36:37], v[174:175]
	global_store_dwordx4 v[220:221], v[38:41], off offset:512 nt
	global_store_dwordx4 v[220:221], v[34:37], off offset:528 nt
	s_mov_b64 s[20:21], 0x20000
	v_lshl_add_u64 v[220:221], v[220:221], 0, s[20:21]
	s_waitcnt vmcnt(16)
	v_pk_add_f32 v[30:31], v[30:31], v[176:177]
	v_pk_add_f32 v[32:33], v[32:33], v[178:179]
	v_pk_add_f32 v[26:27], v[26:27], v[188:189]
	v_pk_add_f32 v[28:29], v[28:29], v[190:191]
	global_store_dwordx4 v[220:221], v[30:33], off nt
	global_store_dwordx4 v[220:221], v[26:29], off offset:16 nt
	v_pk_add_f32 v[22:23], v[22:23], v[192:193]
	v_pk_add_f32 v[24:25], v[24:25], v[194:195]
	v_pk_add_f32 v[18:19], v[18:19], v[196:197]
	v_pk_add_f32 v[20:21], v[20:21], v[198:199]
	global_store_dwordx4 v[220:221], v[22:25], off offset:512 nt
	global_store_dwordx4 v[220:221], v[18:21], off offset:528 nt
	s_mov_b64 s[20:21], 0x20000
	v_lshl_add_u64 v[220:221], v[220:221], 0, s[20:21]
	s_waitcnt vmcnt(12)
	v_pk_add_f32 v[14:15], v[14:15], v[200:201]
	v_pk_add_f32 v[16:17], v[16:17], v[202:203]
	v_pk_add_f32 v[10:11], v[10:11], v[206:207]
	v_pk_add_f32 v[12:13], v[12:13], v[208:209]
	global_store_dwordx4 v[220:221], v[14:17], off nt
	global_store_dwordx4 v[220:221], v[10:13], off offset:16 nt
	v_pk_add_f32 v[6:7], v[6:7], v[210:211]
	v_pk_add_f32 v[8:9], v[8:9], v[212:213]
	v_pk_add_f32 v[2:3], v[2:3], v[214:215]
	v_pk_add_f32 v[4:5], v[4:5], v[216:217]
	global_store_dwordx4 v[220:221], v[6:9], off offset:512 nt
	global_store_dwordx4 v[220:221], v[2:5], off offset:528 nt
	s_mov_b64 s[20:21], s[46:47]
	s_cbranch_vccz .LBB0_1440
	s_waitcnt vmcnt(0)
	s_cmpk_gt_u32 s38, 0xff
	s_cbranch_scc1 .LBB0_1451
	s_barrier
